# dense attention: PV MFMAs in ks-major order (consecutive MFMAs hit different O blocks), rest as v51
# baseline (speedup 1.0000x reference)
; #define SBAR() __builtin_amdgcn_sched_barrier(0)
; __device__ __forceinline__ void qkt(f32x16& p0, f32x16& p1, const bf16_t* Ks, const bf16x8* qr, int r32, int hi) {
;   p0 = f32x16{}; p1 = f32x16{};
; #pragma unroll
;   for (int d0 = 0; d0 < 8; ++d0) { int cb = (d0 * 16 + hi * 8) * 2;
;     bf16x8 b0 = *reinterpret_cast<const bf16x8*>((const char*)Ks + KSWZ(r32, cb));
;     bf16x8 b1 = *reinterpret_cast<const bf16x8*>((const char*)Ks + KSWZ(32 + r32, cb));
;     p0 = __builtin_amdgcn_mfma_f32_32x32x16_bf16(b0, qr[d0], p0, 0, 0, 0);
;     p1 = __builtin_amdgcn_mfma_f32_32x32x16_bf16(b1, qr[d0], p1, 0, 0, 0); }
; }
; __device__ __forceinline__ int v_st(int k, int c) { const int kk = (k & ~0xC) | ((k & 4) << 1) | ((k & 8) >> 1); return ((kk >> 3) * 4 + (c >> 5)) * 512 + ((kk & 7) * 32 + (c & 31)) * 2; }
; __device__ __forceinline__ int v_rd_base(int lane) { return ((lane & 3) << 3) | (((lane >> 2) & 3) << 6) | (((lane >> 4) & 1) << 5) | (((lane >> 5) & 1) << 8); }
; template <int OFF> __device__ __forceinline__ s16x4 tr_read(int vb) {
;   s16x4 r; asm volatile("ds_read_b64_tr_b16 %0, %1 offset:%2" : "=&v"(r) : "v"(vb), "i"(OFF) : "memory"); return r;
; }
; template <int D0> __device__ __forceinline__ void pv_one(f32x16& od, int vb, bf16x8 pa0, bf16x8 pa1, bf16x8 pa2, bf16x8 pa3) {
;   const s16x4 l0 = tr_read<v_rd_off(D0, 0, 0)>(vb), h0 = tr_read<v_rd_off(D0, 0, 1)>(vb), l1 = tr_read<v_rd_off(D0, 1, 0)>(vb), h1 = tr_read<v_rd_off(D0, 1, 1)>(vb);
;   const s16x4 l2 = tr_read<v_rd_off(D0, 2, 0)>(vb), h2 = tr_read<v_rd_off(D0, 2, 1)>(vb), l3 = tr_read<v_rd_off(D0, 3, 0)>(vb), h3 = tr_read<v_rd_off(D0, 3, 1)>(vb);
;   asm volatile("s_waitcnt lgkmcnt(0)" ::: "memory"); SBAR();
;     ...
;   od = __builtin_amdgcn_mfma_f32_32x32x16_bf16(pa0, PK(l0, h0), od, 0, 0, 0);
;   od = __builtin_amdgcn_mfma_f32_32x32x16_bf16(pa1, PK(l1, h1), od, 0, 0, 0);
;   od = __builtin_amdgcn_mfma_f32_32x32x16_bf16(pa2, PK(l2, h2), od, 0, 0, 0);
;   od = __builtin_amdgcn_mfma_f32_32x32x16_bf16(pa3, PK(l3, h3), od, 0, 0, 0);
;     ...
; }
; __device__ __forceinline__ void pv_d0(f32x16* o, int vb, bf16x8 pa0, bf16x8 pa1, bf16x8 pa2, bf16x8 pa3) {
;   pv_one<0>(o[0], vb, pa0, pa1, pa2, pa3); pv_one<1>(o[1], vb, pa0, pa1, pa2, pa3); pv_one<2>(o[2], vb, pa0, pa1, pa2, pa3); pv_one<3>(o[3], vb, pa0, pa1, pa2, pa3);
.Lda_loop:
	s_setprio 3
	s_waitcnt vmcnt(4)
	ds_write_b128 v197, v[134:137] offset:32768
	ds_write_b128 v197, v[138:141] offset:40960
	ds_write_b128 v185, v[142:145] offset:32768
	ds_write_b128 v185, v[146:149] offset:40960
	s_waitcnt lgkmcnt(10)
	v_mfma_f32_32x32x16_bf16 v[80:95], v[150:153], v[130:133], 0
	v_mfma_f32_32x32x16_bf16 v[64:79], v[154:157], v[130:133], 0
	global_load_dwordx4 v[134:137], v184, s[16:17]
	global_load_dwordx4 v[138:141], v184, s[2:3]
	global_load_dwordx4 v[142:145], v184, s[14:15]
	global_load_dwordx4 v[146:149], v184, s[10:11]
	s_add_u32 s16, s16, 0x60000
	s_addc_u32 s17, s17, 0
	s_add_u32 s2, s2, 0x60000
	s_addc_u32 s3, s3, 0
	s_add_u32 s14, s14, 0x60000
	s_addc_u32 s15, s15, 0
	s_add_u32 s10, s10, 0x60000
	s_addc_u32 s11, s11, 0
	ds_read_b128 v[150:153], v208 offset:0
	ds_read_b128 v[154:157], v208 offset:8192
	s_waitcnt lgkmcnt(10)
	v_mfma_f32_32x32x16_bf16 v[80:95], v[158:161], v[126:129], v[80:95]
	v_mfma_f32_32x32x16_bf16 v[64:79], v[162:165], v[126:129], v[64:79]
	ds_read_b128 v[158:161], v209 offset:0
	ds_read_b128 v[162:165], v209 offset:8192
	s_waitcnt lgkmcnt(10)
	v_mfma_f32_32x32x16_bf16 v[80:95], v[228:231], v[122:125], v[80:95]
	v_mfma_f32_32x32x16_bf16 v[64:79], v[232:235], v[122:125], v[64:79]
	ds_read_b128 v[228:231], v210 offset:0
	ds_read_b128 v[232:235], v210 offset:8192
	s_waitcnt lgkmcnt(10)
	v_mfma_f32_32x32x16_bf16 v[80:95], v[236:239], v[118:121], v[80:95]
	v_mfma_f32_32x32x16_bf16 v[64:79], v[240:243], v[118:121], v[64:79]
	ds_read_b128 v[236:239], v211 offset:0
	ds_read_b128 v[240:243], v211 offset:8192
	s_waitcnt lgkmcnt(6)
	v_mfma_f32_32x32x16_bf16 v[80:95], v[150:153], v[114:117], v[80:95]
	v_mfma_f32_32x32x16_bf16 v[64:79], v[154:157], v[114:117], v[64:79]
	ds_read_b64_tr_b16 v[150:151], v196 offset:49152
	ds_read_b64_tr_b16 v[152:153], v196 offset:51200
	ds_read_b64_tr_b16 v[154:155], v196 offset:49664
	ds_read_b64_tr_b16 v[156:157], v196 offset:51712
	s_waitcnt lgkmcnt(8)
	v_mfma_f32_32x32x16_bf16 v[80:95], v[158:161], v[110:113], v[80:95]
	v_mfma_f32_32x32x16_bf16 v[64:79], v[162:165], v[110:113], v[64:79]
	ds_read_b64_tr_b16 v[158:159], v196 offset:50176
	ds_read_b64_tr_b16 v[160:161], v196 offset:52224
	ds_read_b64_tr_b16 v[162:163], v196 offset:50688
	ds_read_b64_tr_b16 v[164:165], v196 offset:52736
	s_waitcnt lgkmcnt(10)
	v_mfma_f32_32x32x16_bf16 v[80:95], v[228:231], v[106:109], v[80:95]
	v_mfma_f32_32x32x16_bf16 v[64:79], v[232:235], v[106:109], v[64:79]
	ds_read_b64_tr_b16 v[228:229], v196 offset:53248
	ds_read_b64_tr_b16 v[230:231], v196 offset:55296
	ds_read_b64_tr_b16 v[232:233], v196 offset:53760
	ds_read_b64_tr_b16 v[234:235], v196 offset:55808
	s_waitcnt lgkmcnt(12)
	v_mfma_f32_32x32x16_bf16 v[80:95], v[236:239], v[102:105], v[80:95]
	v_mfma_f32_32x32x16_bf16 v[64:79], v[240:243], v[102:105], v[64:79]
	ds_read_b64_tr_b16 v[236:237], v196 offset:54272
	ds_read_b64_tr_b16 v[238:239], v196 offset:56320
	s_waitcnt lgkmcnt(12)
	v_mfma_f32_32x32x16_bf16 v[0:15], v[166:169], v[150:153], v[0:15]
	ds_read_b64_tr_b16 v[240:241], v196 offset:54784
	ds_read_b64_tr_b16 v[242:243], v196 offset:56832
	s_waitcnt lgkmcnt(12)
	v_mfma_f32_32x32x16_bf16 v[48:63], v[166:169], v[154:157], v[48:63]
	ds_read_b64_tr_b16 v[150:151], v196 offset:57344
	ds_read_b64_tr_b16 v[152:153], v196 offset:59392
	s_waitcnt lgkmcnt(12)
	v_mfma_f32_32x32x16_bf16 v[32:47], v[166:169], v[158:161], v[32:47]
	ds_read_b64_tr_b16 v[154:155], v196 offset:57856
	ds_read_b64_tr_b16 v[156:157], v196 offset:59904
	s_waitcnt lgkmcnt(12)
	v_mfma_f32_32x32x16_bf16 v[16:31], v[166:169], v[162:165], v[16:31]
	ds_read_b64_tr_b16 v[158:159], v196 offset:58368
	ds_read_b64_tr_b16 v[160:161], v196 offset:60416
	s_waitcnt lgkmcnt(12)
	v_mfma_f32_32x32x16_bf16 v[0:15], v[170:173], v[228:231], v[0:15]
	ds_read_b64_tr_b16 v[162:163], v196 offset:58880
	ds_read_b64_tr_b16 v[164:165], v196 offset:60928
	s_waitcnt lgkmcnt(12)
	v_mfma_f32_32x32x16_bf16 v[48:63], v[170:173], v[232:235], v[48:63]
	ds_read_b64_tr_b16 v[228:229], v196 offset:61440
	ds_read_b64_tr_b16 v[230:231], v196 offset:63488
	s_waitcnt lgkmcnt(12)
	v_mfma_f32_32x32x16_bf16 v[32:47], v[170:173], v[236:239], v[32:47]
	ds_read_b64_tr_b16 v[232:233], v196 offset:61952
	ds_read_b64_tr_b16 v[234:235], v196 offset:64000
	s_waitcnt lgkmcnt(12)
	v_mfma_f32_32x32x16_bf16 v[16:31], v[170:173], v[240:243], v[16:31]
	ds_read_b64_tr_b16 v[236:237], v196 offset:62464
	ds_read_b64_tr_b16 v[238:239], v196 offset:64512
	s_waitcnt lgkmcnt(12)
	v_mfma_f32_32x32x16_bf16 v[0:15], v[176:179], v[150:153], v[0:15]
	ds_read_b64_tr_b16 v[240:241], v196 offset:62976
	ds_read_b64_tr_b16 v[242:243], v196 offset:65024
	s_waitcnt lgkmcnt(12)
	v_mfma_f32_32x32x16_bf16 v[48:63], v[176:179], v[154:157], v[48:63]
	s_waitcnt lgkmcnt(10)
	v_mfma_f32_32x32x16_bf16 v[32:47], v[176:179], v[158:161], v[32:47]
	s_waitcnt lgkmcnt(8)
	v_mfma_f32_32x32x16_bf16 v[16:31], v[176:179], v[162:165], v[16:31]
	s_waitcnt lgkmcnt(6)
	v_mfma_f32_32x32x16_bf16 v[0:15], v[180:183], v[228:231], v[0:15]
	s_waitcnt lgkmcnt(4)
	v_mfma_f32_32x32x16_bf16 v[48:63], v[180:183], v[232:235], v[48:63]
	s_waitcnt lgkmcnt(2)
	v_mfma_f32_32x32x16_bf16 v[32:47], v[180:183], v[236:239], v[32:47]
	s_waitcnt lgkmcnt(0)
	v_mfma_f32_32x32x16_bf16 v[16:31], v[180:183], v[240:243], v[16:31]
	s_setprio 0

; #define SBAR() __builtin_amdgcn_sched_barrier(0)
; __device__ __forceinline__ void qkt(f32x16& p0, f32x16& p1, const bf16_t* Ks, const bf16x8* qr, int r32, int hi) {
;   p0 = f32x16{}; p1 = f32x16{};
; #pragma unroll
;   for (int d0 = 0; d0 < 8; ++d0) { int cb = (d0 * 16 + hi * 8) * 2;
;     bf16x8 b0 = *reinterpret_cast<const bf16x8*>((const char*)Ks + KSWZ(r32, cb));
;     bf16x8 b1 = *reinterpret_cast<const bf16x8*>((const char*)Ks + KSWZ(32 + r32, cb));
;     p0 = __builtin_amdgcn_mfma_f32_32x32x16_bf16(b0, qr[d0], p0, 0, 0, 0);
;     p1 = __builtin_amdgcn_mfma_f32_32x32x16_bf16(b1, qr[d0], p1, 0, 0, 0); }
; }
; __device__ __forceinline__ int v_st(int k, int c) { const int kk = (k & ~0xC) | ((k & 4) << 1) | ((k & 8) >> 1); return ((kk >> 3) * 4 + (c >> 5)) * 512 + ((kk & 7) * 32 + (c & 31)) * 2; }
; __device__ __forceinline__ int v_rd_base(int lane) { return ((lane & 3) << 3) | (((lane >> 2) & 3) << 6) | (((lane >> 4) & 1) << 5) | (((lane >> 5) & 1) << 8); }
; template <int OFF> __device__ __forceinline__ s16x4 tr_read(int vb) {
;   s16x4 r; asm volatile("ds_read_b64_tr_b16 %0, %1 offset:%2" : "=&v"(r) : "v"(vb), "i"(OFF) : "memory"); return r;
; }
; template <int D0> __device__ __forceinline__ void pv_one(f32x16& od, int vb, bf16x8 pa0, bf16x8 pa1, bf16x8 pa2, bf16x8 pa3) {
;   const s16x4 l0 = tr_read<v_rd_off(D0, 0, 0)>(vb), h0 = tr_read<v_rd_off(D0, 0, 1)>(vb), l1 = tr_read<v_rd_off(D0, 1, 0)>(vb), h1 = tr_read<v_rd_off(D0, 1, 1)>(vb);
;   const s16x4 l2 = tr_read<v_rd_off(D0, 2, 0)>(vb), h2 = tr_read<v_rd_off(D0, 2, 1)>(vb), l3 = tr_read<v_rd_off(D0, 3, 0)>(vb), h3 = tr_read<v_rd_off(D0, 3, 1)>(vb);
;   asm volatile("s_waitcnt lgkmcnt(0)" ::: "memory"); SBAR();
;     ...
;   od = __builtin_amdgcn_mfma_f32_32x32x16_bf16(pa0, PK(l0, h0), od, 0, 0, 0);
;   od = __builtin_amdgcn_mfma_f32_32x32x16_bf16(pa1, PK(l1, h1), od, 0, 0, 0);
;   od = __builtin_amdgcn_mfma_f32_32x32x16_bf16(pa2, PK(l2, h2), od, 0, 0, 0);
;   od = __builtin_amdgcn_mfma_f32_32x32x16_bf16(pa3, PK(l3, h3), od, 0, 0, 0);
;     ...
; }
; __device__ __forceinline__ void pv_d0(f32x16* o, int vb, bf16x8 pa0, bf16x8 pa1, bf16x8 pa2, bf16x8 pa3) {
;   pv_one<0>(o[0], vb, pa0, pa1, pa2, pa3); pv_one<1>(o[1], vb, pa0, pa1, pa2, pa3); pv_one<2>(o[2], vb, pa0, pa1, pa2, pa3); pv_one<3>(o[3], vb, pa0, pa1, pa2, pa3);
.Lda_skipk_0:
	s_barrier
	s_setprio 3
	s_waitcnt vmcnt(4)
	ds_write_b128 v197, v[186:189] offset:49152
	ds_write_b128 v197, v[220:223] offset:57344
	ds_write_b128 v185, v[246:249] offset:49152
	ds_write_b128 v185, v[200:203] offset:57344
	s_waitcnt lgkmcnt(10)
	v_mfma_f32_32x32x16_bf16 v[80:95], v[150:153], v[130:133], 0
	v_mfma_f32_32x32x16_bf16 v[64:79], v[154:157], v[130:133], 0
	global_load_dwordx4 v[186:189], v184, s[16:17]
	global_load_dwordx4 v[220:223], v184, s[2:3]
	global_load_dwordx4 v[246:249], v184, s[14:15]
	global_load_dwordx4 v[200:203], v184, s[10:11]
	s_add_u32 s16, s16, 0x60000
	s_addc_u32 s17, s17, 0
	s_add_u32 s2, s2, 0x60000
	s_addc_u32 s3, s3, 0
	s_add_u32 s14, s14, 0x60000
	s_addc_u32 s15, s15, 0
	s_add_u32 s10, s10, 0x60000
	s_addc_u32 s11, s11, 0
	ds_read_b128 v[150:153], v208 offset:16384
	ds_read_b128 v[154:157], v208 offset:24576
	s_waitcnt lgkmcnt(10)
	v_mfma_f32_32x32x16_bf16 v[80:95], v[158:161], v[126:129], v[80:95]
	v_mfma_f32_32x32x16_bf16 v[64:79], v[162:165], v[126:129], v[64:79]
	ds_read_b128 v[158:161], v209 offset:16384
	ds_read_b128 v[162:165], v209 offset:24576
	s_waitcnt lgkmcnt(10)
	v_mfma_f32_32x32x16_bf16 v[80:95], v[228:231], v[122:125], v[80:95]
	v_mfma_f32_32x32x16_bf16 v[64:79], v[232:235], v[122:125], v[64:79]
	ds_read_b128 v[228:231], v210 offset:16384
	ds_read_b128 v[232:235], v210 offset:24576
	s_waitcnt lgkmcnt(10)
	v_mfma_f32_32x32x16_bf16 v[80:95], v[236:239], v[118:121], v[80:95]
	v_mfma_f32_32x32x16_bf16 v[64:79], v[240:243], v[118:121], v[64:79]
	ds_read_b128 v[236:239], v211 offset:16384
	ds_read_b128 v[240:243], v211 offset:24576
	s_waitcnt lgkmcnt(6)
	v_mfma_f32_32x32x16_bf16 v[80:95], v[150:153], v[114:117], v[80:95]
	v_mfma_f32_32x32x16_bf16 v[64:79], v[154:157], v[114:117], v[64:79]
	ds_read_b64_tr_b16 v[150:151], v196 offset:0
	ds_read_b64_tr_b16 v[152:153], v196 offset:2048
	ds_read_b64_tr_b16 v[154:155], v196 offset:512
	ds_read_b64_tr_b16 v[156:157], v196 offset:2560
	s_waitcnt lgkmcnt(8)
	v_mfma_f32_32x32x16_bf16 v[80:95], v[158:161], v[110:113], v[80:95]
	v_mfma_f32_32x32x16_bf16 v[64:79], v[162:165], v[110:113], v[64:79]
	ds_read_b64_tr_b16 v[158:159], v196 offset:1024
	ds_read_b64_tr_b16 v[160:161], v196 offset:3072
	ds_read_b64_tr_b16 v[162:163], v196 offset:1536
	ds_read_b64_tr_b16 v[164:165], v196 offset:3584
	s_waitcnt lgkmcnt(10)
	v_mfma_f32_32x32x16_bf16 v[80:95], v[228:231], v[106:109], v[80:95]
	v_mfma_f32_32x32x16_bf16 v[64:79], v[232:235], v[106:109], v[64:79]
	ds_read_b64_tr_b16 v[228:229], v196 offset:4096
	ds_read_b64_tr_b16 v[230:231], v196 offset:6144
	ds_read_b64_tr_b16 v[232:233], v196 offset:4608
	ds_read_b64_tr_b16 v[234:235], v196 offset:6656
	s_waitcnt lgkmcnt(12)
	v_mfma_f32_32x32x16_bf16 v[80:95], v[236:239], v[102:105], v[80:95]
	v_mfma_f32_32x32x16_bf16 v[64:79], v[240:243], v[102:105], v[64:79]
	ds_read_b64_tr_b16 v[236:237], v196 offset:5120
	ds_read_b64_tr_b16 v[238:239], v196 offset:7168
	s_waitcnt lgkmcnt(12)
	v_mfma_f32_32x32x16_bf16 v[0:15], v[166:169], v[150:153], v[0:15]
	ds_read_b64_tr_b16 v[240:241], v196 offset:5632
	ds_read_b64_tr_b16 v[242:243], v196 offset:7680
	s_waitcnt lgkmcnt(12)
	v_mfma_f32_32x32x16_bf16 v[48:63], v[166:169], v[154:157], v[48:63]
	ds_read_b64_tr_b16 v[150:151], v196 offset:8192
	ds_read_b64_tr_b16 v[152:153], v196 offset:10240
	s_waitcnt lgkmcnt(12)
	v_mfma_f32_32x32x16_bf16 v[32:47], v[166:169], v[158:161], v[32:47]
	ds_read_b64_tr_b16 v[154:155], v196 offset:8704
	ds_read_b64_tr_b16 v[156:157], v196 offset:10752
	s_waitcnt lgkmcnt(12)
	v_mfma_f32_32x32x16_bf16 v[16:31], v[166:169], v[162:165], v[16:31]
	ds_read_b64_tr_b16 v[158:159], v196 offset:9216
	ds_read_b64_tr_b16 v[160:161], v196 offset:11264
	s_waitcnt lgkmcnt(12)
	v_mfma_f32_32x32x16_bf16 v[0:15], v[170:173], v[228:231], v[0:15]
	ds_read_b64_tr_b16 v[162:163], v196 offset:9728
	ds_read_b64_tr_b16 v[164:165], v196 offset:11776
	s_waitcnt lgkmcnt(12)
	v_mfma_f32_32x32x16_bf16 v[48:63], v[170:173], v[232:235], v[48:63]
	ds_read_b64_tr_b16 v[228:229], v196 offset:12288
	ds_read_b64_tr_b16 v[230:231], v196 offset:14336
	s_waitcnt lgkmcnt(12)
	v_mfma_f32_32x32x16_bf16 v[32:47], v[170:173], v[236:239], v[32:47]
	ds_read_b64_tr_b16 v[232:233], v196 offset:12800
	ds_read_b64_tr_b16 v[234:235], v196 offset:14848
	s_waitcnt lgkmcnt(12)
	v_mfma_f32_32x32x16_bf16 v[16:31], v[170:173], v[240:243], v[16:31]
	ds_read_b64_tr_b16 v[236:237], v196 offset:13312
	ds_read_b64_tr_b16 v[238:239], v196 offset:15360
	s_waitcnt lgkmcnt(12)
	v_mfma_f32_32x32x16_bf16 v[0:15], v[176:179], v[150:153], v[0:15]
	ds_read_b64_tr_b16 v[240:241], v196 offset:13824
	ds_read_b64_tr_b16 v[242:243], v196 offset:15872
	s_waitcnt lgkmcnt(12)
	v_mfma_f32_32x32x16_bf16 v[48:63], v[176:179], v[154:157], v[48:63]
	s_waitcnt lgkmcnt(10)
	v_mfma_f32_32x32x16_bf16 v[32:47], v[176:179], v[158:161], v[32:47]
	s_waitcnt lgkmcnt(8)
	v_mfma_f32_32x32x16_bf16 v[16:31], v[176:179], v[162:165], v[16:31]
	s_waitcnt lgkmcnt(6)
	v_mfma_f32_32x32x16_bf16 v[0:15], v[180:183], v[228:231], v[0:15]
	s_waitcnt lgkmcnt(4)
	v_mfma_f32_32x32x16_bf16 v[48:63], v[180:183], v[232:235], v[48:63]
	s_waitcnt lgkmcnt(2)
	v_mfma_f32_32x32x16_bf16 v[32:47], v[180:183], v[236:239], v[32:47]
	s_waitcnt lgkmcnt(0)
	v_mfma_f32_32x32x16_bf16 v[16:31], v[180:183], v[240:243], v[16:31]
	s_setprio 0
	s_barrier
; __device__ __forceinline__ void partialSM(f32x16& p0, f32x16& p1, float& m_reg, float& mn, float& alpha) {
;     ...
;   float pmax = p0[0];
; #pragma unroll
;   for (int r = 1; r < 16; ++r) pmax = fmaxf(pmax, p0[r]);
; #pragma unroll
;   for (int r = 0; r < 16; ++r) pmax = fmaxf(pmax, p1[r]);
;   { auto rr = __builtin_amdgcn_permlane32_swap(__float_as_uint(pmax), __float_as_uint(pmax), false, false);
;     pmax = fmaxf(__uint_as_float(rr[0]), __uint_as_float(rr[1])); }
;   if (__builtin_expect(__all(pmax - m_reg <= THR / SCALE), 1)) { mn = m_reg; alpha = 1.f; }
;   else { mn = fmaxf(m_reg, pmax); alpha = __builtin_amdgcn_exp2f((m_reg - mn) * C); m_reg = mn; }
	v_max3_f32 v190, v80, v81, v82
	v_max3_f32 v191, v64, v65, v66
	v_max3_f32 v190, v190, v83, v84
	v_max3_f32 v191, v191, v67, v68
	v_max3_f32 v190, v190, v85, v86
	v_max3_f32 v191, v191, v69, v70
	v_max3_f32 v190, v190, v87, v88
	v_max3_f32 v191, v191, v71, v72
	v_max3_f32 v190, v190, v89, v90
	v_max3_f32 v191, v191, v73, v74
	v_max3_f32 v190, v190, v91, v92
	v_max3_f32 v191, v191, v75, v76
	v_max3_f32 v190, v190, v93, v94
	v_max3_f32 v191, v191, v77, v78
	v_max3_f32 v190, v190, v95, v79
	v_max_f32_e32 v190, v190, v191
	v_sub_f32_e32 v215, v190, v174
	v_cmp_ge_f32_e32 vcc, s86, v215
	s_nop 0
	s_cmp_eq_u64 vcc, exec
	s_cbranch_scc1 .Lda_common_1
	v_mov_b32_e32 v191, v190
	s_nop 1
	v_permlane32_swap_b32_e32 v190, v191
	s_nop 0
	v_max_f32_e32 v212, v190, v191
	v_max_f32_e32 v191, v174, v212
	v_sub_f32_e32 v215, v174, v191
	v_mul_f32_e32 v215, s92, v215
	v_exp_f32_e32 v213, v215
	v_mov_b32_e32 v174, v191
	v_mul_f32_e32 v214, 0xbe0293ee, v174
	v_mul_f32_e32 v175, v175, v213
	s_and_saveexec_b64 s[12:13], s[40:41]
	ds_write_b32 v199, v213 offset:128
	s_or_b64 exec, exec, s[12:13]
	s_waitcnt lgkmcnt(0)
	v_add_u32_e32 v215, v99, v96
	ds_read_b128 v[228:231], v215 offset:128
	ds_read_b128 v[232:235], v215 offset:160
	ds_read_b128 v[236:239], v215 offset:192
	ds_read_b128 v[240:243], v215 offset:224
	s_waitcnt lgkmcnt(0)
	v_pk_mul_f32 v[0:1], v[0:1], v[228:229]
	v_pk_mul_f32 v[2:3], v[2:3], v[230:231]
	v_pk_mul_f32 v[4:5], v[4:5], v[232:233]
	v_pk_mul_f32 v[6:7], v[6:7], v[234:235]
	v_pk_mul_f32 v[8:9], v[8:9], v[236:237]
	v_pk_mul_f32 v[10:11], v[10:11], v[238:239]
	v_pk_mul_f32 v[12:13], v[12:13], v[240:241]
	v_pk_mul_f32 v[14:15], v[14:15], v[242:243]
	v_pk_mul_f32 v[48:49], v[48:49], v[228:229]
	v_pk_mul_f32 v[50:51], v[50:51], v[230:231]
	v_pk_mul_f32 v[52:53], v[52:53], v[232:233]
	v_pk_mul_f32 v[54:55], v[54:55], v[234:235]
	v_pk_mul_f32 v[56:57], v[56:57], v[236:237]
	v_pk_mul_f32 v[58:59], v[58:59], v[238:239]
	v_pk_mul_f32 v[60:61], v[60:61], v[240:241]
	v_pk_mul_f32 v[62:63], v[62:63], v[242:243]
	v_pk_mul_f32 v[32:33], v[32:33], v[228:229]
	v_pk_mul_f32 v[34:35], v[34:35], v[230:231]
	v_pk_mul_f32 v[36:37], v[36:37], v[232:233]
	v_pk_mul_f32 v[38:39], v[38:39], v[234:235]
	v_pk_mul_f32 v[40:41], v[40:41], v[236:237]
	v_pk_mul_f32 v[42:43], v[42:43], v[238:239]
	v_pk_mul_f32 v[44:45], v[44:45], v[240:241]
	v_pk_mul_f32 v[46:47], v[46:47], v[242:243]
	v_pk_mul_f32 v[16:17], v[16:17], v[228:229]
	v_pk_mul_f32 v[18:19], v[18:19], v[230:231]
	v_pk_mul_f32 v[20:21], v[20:21], v[232:233]
	v_pk_mul_f32 v[22:23], v[22:23], v[234:235]
	v_pk_mul_f32 v[24:25], v[24:25], v[236:237]
	v_pk_mul_f32 v[26:27], v[26:27], v[238:239]
	v_pk_mul_f32 v[28:29], v[28:29], v[240:241]
	v_pk_mul_f32 v[30:31], v[30:31], v[242:243]

; #define SBAR() __builtin_amdgcn_sched_barrier(0)
; __device__ __forceinline__ void qkt(f32x16& p0, f32x16& p1, const bf16_t* Ks, const bf16x8* qr, int r32, int hi) {
;   p0 = f32x16{}; p1 = f32x16{};
; #pragma unroll
;   for (int d0 = 0; d0 < 8; ++d0) { int cb = (d0 * 16 + hi * 8) * 2;
;     bf16x8 b0 = *reinterpret_cast<const bf16x8*>((const char*)Ks + KSWZ(r32, cb));
;     bf16x8 b1 = *reinterpret_cast<const bf16x8*>((const char*)Ks + KSWZ(32 + r32, cb));
;     p0 = __builtin_amdgcn_mfma_f32_32x32x16_bf16(b0, qr[d0], p0, 0, 0, 0);
;     p1 = __builtin_amdgcn_mfma_f32_32x32x16_bf16(b1, qr[d0], p1, 0, 0, 0); }
; }
; __device__ __forceinline__ int v_st(int k, int c) { const int kk = (k & ~0xC) | ((k & 4) << 1) | ((k & 8) >> 1); return ((kk >> 3) * 4 + (c >> 5)) * 512 + ((kk & 7) * 32 + (c & 31)) * 2; }
; __device__ __forceinline__ int v_rd_base(int lane) { return ((lane & 3) << 3) | (((lane >> 2) & 3) << 6) | (((lane >> 4) & 1) << 5) | (((lane >> 5) & 1) << 8); }
; template <int OFF> __device__ __forceinline__ s16x4 tr_read(int vb) {
;   s16x4 r; asm volatile("ds_read_b64_tr_b16 %0, %1 offset:%2" : "=&v"(r) : "v"(vb), "i"(OFF) : "memory"); return r;
; }
; template <int D0> __device__ __forceinline__ void pv_one(f32x16& od, int vb, bf16x8 pa0, bf16x8 pa1, bf16x8 pa2, bf16x8 pa3) {
;   const s16x4 l0 = tr_read<v_rd_off(D0, 0, 0)>(vb), h0 = tr_read<v_rd_off(D0, 0, 1)>(vb), l1 = tr_read<v_rd_off(D0, 1, 0)>(vb), h1 = tr_read<v_rd_off(D0, 1, 1)>(vb);
;   const s16x4 l2 = tr_read<v_rd_off(D0, 2, 0)>(vb), h2 = tr_read<v_rd_off(D0, 2, 1)>(vb), l3 = tr_read<v_rd_off(D0, 3, 0)>(vb), h3 = tr_read<v_rd_off(D0, 3, 1)>(vb);
;   asm volatile("s_waitcnt lgkmcnt(0)" ::: "memory"); SBAR();
;     ...
;   od = __builtin_amdgcn_mfma_f32_32x32x16_bf16(pa0, PK(l0, h0), od, 0, 0, 0);
;   od = __builtin_amdgcn_mfma_f32_32x32x16_bf16(pa1, PK(l1, h1), od, 0, 0, 0);
;   od = __builtin_amdgcn_mfma_f32_32x32x16_bf16(pa2, PK(l2, h2), od, 0, 0, 0);
;   od = __builtin_amdgcn_mfma_f32_32x32x16_bf16(pa3, PK(l3, h3), od, 0, 0, 0);
;     ...
; }
; __device__ __forceinline__ void pv_d0(f32x16* o, int vb, bf16x8 pa0, bf16x8 pa1, bf16x8 pa2, bf16x8 pa3) {
;   pv_one<0>(o[0], vb, pa0, pa1, pa2, pa3); pv_one<1>(o[1], vb, pa0, pa1, pa2, pa3); pv_one<2>(o[2], vb, pa0, pa1, pa2, pa3); pv_one<3>(o[3], vb, pa0, pa1, pa2, pa3);
.Lda_skipk_1:
	s_barrier
	s_setprio 3
	s_waitcnt vmcnt(4)
	ds_write_b128 v197, v[134:137] offset:0
	ds_write_b128 v197, v[138:141] offset:8192
	ds_write_b128 v185, v[142:145] offset:0
	ds_write_b128 v185, v[146:149] offset:8192
	s_waitcnt lgkmcnt(10)
	v_mfma_f32_32x32x16_bf16 v[80:95], v[150:153], v[130:133], 0
	v_mfma_f32_32x32x16_bf16 v[64:79], v[154:157], v[130:133], 0
	global_load_dwordx4 v[134:137], v184, s[16:17]
	global_load_dwordx4 v[138:141], v184, s[2:3]
	global_load_dwordx4 v[142:145], v184, s[14:15]
	global_load_dwordx4 v[146:149], v184, s[10:11]
	s_add_u32 s16, s16, 0x60000
	s_addc_u32 s17, s17, 0
	s_add_u32 s2, s2, 0x60000
	s_addc_u32 s3, s3, 0
	s_add_u32 s14, s14, 0x60000
	s_addc_u32 s15, s15, 0
	s_add_u32 s10, s10, 0x60000
	s_addc_u32 s11, s11, 0
	ds_read_b128 v[150:153], v208 offset:32768
	ds_read_b128 v[154:157], v208 offset:40960
	s_waitcnt lgkmcnt(10)
	v_mfma_f32_32x32x16_bf16 v[80:95], v[158:161], v[126:129], v[80:95]
	v_mfma_f32_32x32x16_bf16 v[64:79], v[162:165], v[126:129], v[64:79]
	ds_read_b128 v[158:161], v209 offset:32768
	ds_read_b128 v[162:165], v209 offset:40960
	s_waitcnt lgkmcnt(10)
	v_mfma_f32_32x32x16_bf16 v[80:95], v[228:231], v[122:125], v[80:95]
	v_mfma_f32_32x32x16_bf16 v[64:79], v[232:235], v[122:125], v[64:79]
	ds_read_b128 v[228:231], v210 offset:32768
	ds_read_b128 v[232:235], v210 offset:40960
	s_waitcnt lgkmcnt(10)
	v_mfma_f32_32x32x16_bf16 v[80:95], v[236:239], v[118:121], v[80:95]
	v_mfma_f32_32x32x16_bf16 v[64:79], v[240:243], v[118:121], v[64:79]
	ds_read_b128 v[236:239], v211 offset:32768
	ds_read_b128 v[240:243], v211 offset:40960
	s_waitcnt lgkmcnt(6)
	v_mfma_f32_32x32x16_bf16 v[80:95], v[150:153], v[114:117], v[80:95]
	v_mfma_f32_32x32x16_bf16 v[64:79], v[154:157], v[114:117], v[64:79]
	ds_read_b64_tr_b16 v[150:151], v196 offset:16384
	ds_read_b64_tr_b16 v[152:153], v196 offset:18432
	ds_read_b64_tr_b16 v[154:155], v196 offset:16896
	ds_read_b64_tr_b16 v[156:157], v196 offset:18944
	s_waitcnt lgkmcnt(8)
	v_mfma_f32_32x32x16_bf16 v[80:95], v[158:161], v[110:113], v[80:95]
	v_mfma_f32_32x32x16_bf16 v[64:79], v[162:165], v[110:113], v[64:79]
	ds_read_b64_tr_b16 v[158:159], v196 offset:17408
	ds_read_b64_tr_b16 v[160:161], v196 offset:19456
	ds_read_b64_tr_b16 v[162:163], v196 offset:17920
	ds_read_b64_tr_b16 v[164:165], v196 offset:19968
	s_waitcnt lgkmcnt(10)
	v_mfma_f32_32x32x16_bf16 v[80:95], v[228:231], v[106:109], v[80:95]
	v_mfma_f32_32x32x16_bf16 v[64:79], v[232:235], v[106:109], v[64:79]
	ds_read_b64_tr_b16 v[228:229], v196 offset:20480
	ds_read_b64_tr_b16 v[230:231], v196 offset:22528
	ds_read_b64_tr_b16 v[232:233], v196 offset:20992
	ds_read_b64_tr_b16 v[234:235], v196 offset:23040
	s_waitcnt lgkmcnt(12)
	v_mfma_f32_32x32x16_bf16 v[80:95], v[236:239], v[102:105], v[80:95]
	v_mfma_f32_32x32x16_bf16 v[64:79], v[240:243], v[102:105], v[64:79]
	ds_read_b64_tr_b16 v[236:237], v196 offset:21504
	ds_read_b64_tr_b16 v[238:239], v196 offset:23552
	s_waitcnt lgkmcnt(12)
	v_mfma_f32_32x32x16_bf16 v[0:15], v[166:169], v[150:153], v[0:15]
	ds_read_b64_tr_b16 v[240:241], v196 offset:22016
	ds_read_b64_tr_b16 v[242:243], v196 offset:24064
	s_waitcnt lgkmcnt(12)
	v_mfma_f32_32x32x16_bf16 v[48:63], v[166:169], v[154:157], v[48:63]
	ds_read_b64_tr_b16 v[150:151], v196 offset:24576
	ds_read_b64_tr_b16 v[152:153], v196 offset:26624
	s_waitcnt lgkmcnt(12)
	v_mfma_f32_32x32x16_bf16 v[32:47], v[166:169], v[158:161], v[32:47]
	ds_read_b64_tr_b16 v[154:155], v196 offset:25088
	ds_read_b64_tr_b16 v[156:157], v196 offset:27136
	s_waitcnt lgkmcnt(12)
	v_mfma_f32_32x32x16_bf16 v[16:31], v[166:169], v[162:165], v[16:31]
	ds_read_b64_tr_b16 v[158:159], v196 offset:25600
	ds_read_b64_tr_b16 v[160:161], v196 offset:27648
	s_waitcnt lgkmcnt(12)
	v_mfma_f32_32x32x16_bf16 v[0:15], v[170:173], v[228:231], v[0:15]
	ds_read_b64_tr_b16 v[162:163], v196 offset:26112
	ds_read_b64_tr_b16 v[164:165], v196 offset:28160
	s_waitcnt lgkmcnt(12)
	v_mfma_f32_32x32x16_bf16 v[48:63], v[170:173], v[232:235], v[48:63]
	ds_read_b64_tr_b16 v[228:229], v196 offset:28672
	ds_read_b64_tr_b16 v[230:231], v196 offset:30720
	s_waitcnt lgkmcnt(12)
	v_mfma_f32_32x32x16_bf16 v[32:47], v[170:173], v[236:239], v[32:47]
	ds_read_b64_tr_b16 v[232:233], v196 offset:29184
	ds_read_b64_tr_b16 v[234:235], v196 offset:31232
	s_waitcnt lgkmcnt(12)
	v_mfma_f32_32x32x16_bf16 v[16:31], v[170:173], v[240:243], v[16:31]
	ds_read_b64_tr_b16 v[236:237], v196 offset:29696
	ds_read_b64_tr_b16 v[238:239], v196 offset:31744
	s_waitcnt lgkmcnt(12)
	v_mfma_f32_32x32x16_bf16 v[0:15], v[176:179], v[150:153], v[0:15]
	ds_read_b64_tr_b16 v[240:241], v196 offset:30208
	ds_read_b64_tr_b16 v[242:243], v196 offset:32256
	s_waitcnt lgkmcnt(12)
	v_mfma_f32_32x32x16_bf16 v[48:63], v[176:179], v[154:157], v[48:63]
	s_waitcnt lgkmcnt(10)
	v_mfma_f32_32x32x16_bf16 v[32:47], v[176:179], v[158:161], v[32:47]
	s_waitcnt lgkmcnt(8)
	v_mfma_f32_32x32x16_bf16 v[16:31], v[176:179], v[162:165], v[16:31]
	s_waitcnt lgkmcnt(6)
	v_mfma_f32_32x32x16_bf16 v[0:15], v[180:183], v[228:231], v[0:15]
	s_waitcnt lgkmcnt(4)
	v_mfma_f32_32x32x16_bf16 v[48:63], v[180:183], v[232:235], v[48:63]
	s_waitcnt lgkmcnt(2)
	v_mfma_f32_32x32x16_bf16 v[32:47], v[180:183], v[236:239], v[32:47]
	s_waitcnt lgkmcnt(0)
	v_mfma_f32_32x32x16_bf16 v[16:31], v[180:183], v[240:243], v[16:31]
	s_setprio 0
	s_barrier
; __device__ __forceinline__ void partialSM(f32x16& p0, f32x16& p1, float& m_reg, float& mn, float& alpha) {
;     ...
;   float pmax = p0[0];
; #pragma unroll
;   for (int r = 1; r < 16; ++r) pmax = fmaxf(pmax, p0[r]);
; #pragma unroll
;   for (int r = 0; r < 16; ++r) pmax = fmaxf(pmax, p1[r]);
;   { auto rr = __builtin_amdgcn_permlane32_swap(__float_as_uint(pmax), __float_as_uint(pmax), false, false);
;     pmax = fmaxf(__uint_as_float(rr[0]), __uint_as_float(rr[1])); }
;   if (__builtin_expect(__all(pmax - m_reg <= THR / SCALE), 1)) { mn = m_reg; alpha = 1.f; }
;   else { mn = fmaxf(m_reg, pmax); alpha = __builtin_amdgcn_exp2f((m_reg - mn) * C); m_reg = mn; }
	v_max3_f32 v190, v80, v81, v82
	v_max3_f32 v191, v64, v65, v66
	v_max3_f32 v190, v190, v83, v84
	v_max3_f32 v191, v191, v67, v68
	v_max3_f32 v190, v190, v85, v86
	v_max3_f32 v191, v191, v69, v70
	v_max3_f32 v190, v190, v87, v88
	v_max3_f32 v191, v191, v71, v72
	v_max3_f32 v190, v190, v89, v90
	v_max3_f32 v191, v191, v73, v74
	v_max3_f32 v190, v190, v91, v92
	v_max3_f32 v191, v191, v75, v76
	v_max3_f32 v190, v190, v93, v94
	v_max3_f32 v191, v191, v77, v78
	v_max3_f32 v190, v190, v95, v79
	v_max_f32_e32 v190, v190, v191
	v_sub_f32_e32 v215, v190, v174
	v_cmp_ge_f32_e32 vcc, s86, v215
	s_nop 0
	s_cmp_eq_u64 vcc, exec
	s_cbranch_scc1 .Lda_common_2
	v_mov_b32_e32 v191, v190
	s_nop 1
	v_permlane32_swap_b32_e32 v190, v191
	s_nop 0
	v_max_f32_e32 v212, v190, v191
	v_max_f32_e32 v191, v174, v212
	v_sub_f32_e32 v215, v174, v191
	v_mul_f32_e32 v215, s92, v215
	v_exp_f32_e32 v213, v215
	v_mov_b32_e32 v174, v191
	v_mul_f32_e32 v214, 0xbe0293ee, v174
	v_mul_f32_e32 v175, v175, v213
	s_and_saveexec_b64 s[12:13], s[40:41]
	ds_write_b32 v199, v213 offset:128
	s_or_b64 exec, exec, s[12:13]
	s_waitcnt lgkmcnt(0)
	v_add_u32_e32 v215, v99, v96
	ds_read_b128 v[228:231], v215 offset:128
	ds_read_b128 v[232:235], v215 offset:160
	ds_read_b128 v[236:239], v215 offset:192
	ds_read_b128 v[240:243], v215 offset:224
	s_waitcnt lgkmcnt(0)
	v_pk_mul_f32 v[0:1], v[0:1], v[228:229]
	v_pk_mul_f32 v[2:3], v[2:3], v[230:231]
	v_pk_mul_f32 v[4:5], v[4:5], v[232:233]
	v_pk_mul_f32 v[6:7], v[6:7], v[234:235]
	v_pk_mul_f32 v[8:9], v[8:9], v[236:237]
	v_pk_mul_f32 v[10:11], v[10:11], v[238:239]
	v_pk_mul_f32 v[12:13], v[12:13], v[240:241]
	v_pk_mul_f32 v[14:15], v[14:15], v[242:243]
	v_pk_mul_f32 v[48:49], v[48:49], v[228:229]
	v_pk_mul_f32 v[50:51], v[50:51], v[230:231]
	v_pk_mul_f32 v[52:53], v[52:53], v[232:233]
	v_pk_mul_f32 v[54:55], v[54:55], v[234:235]
	v_pk_mul_f32 v[56:57], v[56:57], v[236:237]
	v_pk_mul_f32 v[58:59], v[58:59], v[238:239]
	v_pk_mul_f32 v[60:61], v[60:61], v[240:241]
	v_pk_mul_f32 v[62:63], v[62:63], v[242:243]
	v_pk_mul_f32 v[32:33], v[32:33], v[228:229]
	v_pk_mul_f32 v[34:35], v[34:35], v[230:231]
	v_pk_mul_f32 v[36:37], v[36:37], v[232:233]
	v_pk_mul_f32 v[38:39], v[38:39], v[234:235]
	v_pk_mul_f32 v[40:41], v[40:41], v[236:237]
	v_pk_mul_f32 v[42:43], v[42:43], v[238:239]
	v_pk_mul_f32 v[44:45], v[44:45], v[240:241]
	v_pk_mul_f32 v[46:47], v[46:47], v[242:243]
	v_pk_mul_f32 v[16:17], v[16:17], v[228:229]
	v_pk_mul_f32 v[18:19], v[18:19], v[230:231]
	v_pk_mul_f32 v[20:21], v[20:21], v[232:233]
	v_pk_mul_f32 v[22:23], v[22:23], v[234:235]
	v_pk_mul_f32 v[24:25], v[24:25], v[236:237]
	v_pk_mul_f32 v[26:27], v[26:27], v[238:239]
	v_pk_mul_f32 v[28:29], v[28:29], v[240:241]
	v_pk_mul_f32 v[30:31], v[30:31], v[242:243]

; #define SBAR() __builtin_amdgcn_sched_barrier(0)
; __device__ __forceinline__ void qkt(f32x16& p0, f32x16& p1, const bf16_t* Ks, const bf16x8* qr, int r32, int hi) {
;   p0 = f32x16{}; p1 = f32x16{};
; #pragma unroll
;   for (int d0 = 0; d0 < 8; ++d0) { int cb = (d0 * 16 + hi * 8) * 2;
;     bf16x8 b0 = *reinterpret_cast<const bf16x8*>((const char*)Ks + KSWZ(r32, cb));
;     bf16x8 b1 = *reinterpret_cast<const bf16x8*>((const char*)Ks + KSWZ(32 + r32, cb));
;     p0 = __builtin_amdgcn_mfma_f32_32x32x16_bf16(b0, qr[d0], p0, 0, 0, 0);
;     p1 = __builtin_amdgcn_mfma_f32_32x32x16_bf16(b1, qr[d0], p1, 0, 0, 0); }
; }
; __device__ __forceinline__ int v_st(int k, int c) { const int kk = (k & ~0xC) | ((k & 4) << 1) | ((k & 8) >> 1); return ((kk >> 3) * 4 + (c >> 5)) * 512 + ((kk & 7) * 32 + (c & 31)) * 2; }
; __device__ __forceinline__ int v_rd_base(int lane) { return ((lane & 3) << 3) | (((lane >> 2) & 3) << 6) | (((lane >> 4) & 1) << 5) | (((lane >> 5) & 1) << 8); }
; template <int OFF> __device__ __forceinline__ s16x4 tr_read(int vb) {
;   s16x4 r; asm volatile("ds_read_b64_tr_b16 %0, %1 offset:%2" : "=&v"(r) : "v"(vb), "i"(OFF) : "memory"); return r;
; }
; template <int D0> __device__ __forceinline__ void pv_one(f32x16& od, int vb, bf16x8 pa0, bf16x8 pa1, bf16x8 pa2, bf16x8 pa3) {
;   const s16x4 l0 = tr_read<v_rd_off(D0, 0, 0)>(vb), h0 = tr_read<v_rd_off(D0, 0, 1)>(vb), l1 = tr_read<v_rd_off(D0, 1, 0)>(vb), h1 = tr_read<v_rd_off(D0, 1, 1)>(vb);
;   const s16x4 l2 = tr_read<v_rd_off(D0, 2, 0)>(vb), h2 = tr_read<v_rd_off(D0, 2, 1)>(vb), l3 = tr_read<v_rd_off(D0, 3, 0)>(vb), h3 = tr_read<v_rd_off(D0, 3, 1)>(vb);
;   asm volatile("s_waitcnt lgkmcnt(0)" ::: "memory"); SBAR();
;     ...
;   od = __builtin_amdgcn_mfma_f32_32x32x16_bf16(pa0, PK(l0, h0), od, 0, 0, 0);
;   od = __builtin_amdgcn_mfma_f32_32x32x16_bf16(pa1, PK(l1, h1), od, 0, 0, 0);
;   od = __builtin_amdgcn_mfma_f32_32x32x16_bf16(pa2, PK(l2, h2), od, 0, 0, 0);
;   od = __builtin_amdgcn_mfma_f32_32x32x16_bf16(pa3, PK(l3, h3), od, 0, 0, 0);
;     ...
; }
; __device__ __forceinline__ void pv_d0(f32x16* o, int vb, bf16x8 pa0, bf16x8 pa1, bf16x8 pa2, bf16x8 pa3) {
;   pv_one<0>(o[0], vb, pa0, pa1, pa2, pa3); pv_one<1>(o[1], vb, pa0, pa1, pa2, pa3); pv_one<2>(o[2], vb, pa0, pa1, pa2, pa3); pv_one<3>(o[3], vb, pa0, pa1, pa2, pa3);
.Lda_skipk_2:
	s_barrier
	s_setprio 3
	s_waitcnt vmcnt(4)
	ds_write_b128 v197, v[186:189] offset:16384
	ds_write_b128 v197, v[220:223] offset:24576
	ds_write_b128 v185, v[246:249] offset:16384
	ds_write_b128 v185, v[200:203] offset:24576
	s_waitcnt lgkmcnt(10)
	v_mfma_f32_32x32x16_bf16 v[80:95], v[150:153], v[130:133], 0
	v_mfma_f32_32x32x16_bf16 v[64:79], v[154:157], v[130:133], 0
	global_load_dwordx4 v[186:189], v184, s[16:17]
	global_load_dwordx4 v[220:223], v184, s[2:3]
	global_load_dwordx4 v[246:249], v184, s[14:15]
	global_load_dwordx4 v[200:203], v184, s[10:11]
	s_add_u32 s16, s16, 0x60000
	s_addc_u32 s17, s17, 0
	s_add_u32 s2, s2, 0x60000
	s_addc_u32 s3, s3, 0
	s_add_u32 s14, s14, 0x60000
	s_addc_u32 s15, s15, 0
	s_add_u32 s10, s10, 0x60000
	s_addc_u32 s11, s11, 0
	ds_read_b128 v[150:153], v208 offset:49152
	ds_read_b128 v[154:157], v208 offset:57344
	s_waitcnt lgkmcnt(10)
	v_mfma_f32_32x32x16_bf16 v[80:95], v[158:161], v[126:129], v[80:95]
	v_mfma_f32_32x32x16_bf16 v[64:79], v[162:165], v[126:129], v[64:79]
	ds_read_b128 v[158:161], v209 offset:49152
	ds_read_b128 v[162:165], v209 offset:57344
	s_waitcnt lgkmcnt(10)
	v_mfma_f32_32x32x16_bf16 v[80:95], v[228:231], v[122:125], v[80:95]
	v_mfma_f32_32x32x16_bf16 v[64:79], v[232:235], v[122:125], v[64:79]
	ds_read_b128 v[228:231], v210 offset:49152
	ds_read_b128 v[232:235], v210 offset:57344
	s_waitcnt lgkmcnt(10)
	v_mfma_f32_32x32x16_bf16 v[80:95], v[236:239], v[118:121], v[80:95]
	v_mfma_f32_32x32x16_bf16 v[64:79], v[240:243], v[118:121], v[64:79]
	ds_read_b128 v[236:239], v211 offset:49152
	ds_read_b128 v[240:243], v211 offset:57344
	s_waitcnt lgkmcnt(6)
	v_mfma_f32_32x32x16_bf16 v[80:95], v[150:153], v[114:117], v[80:95]
	v_mfma_f32_32x32x16_bf16 v[64:79], v[154:157], v[114:117], v[64:79]
	ds_read_b64_tr_b16 v[150:151], v196 offset:32768
	ds_read_b64_tr_b16 v[152:153], v196 offset:34816
	ds_read_b64_tr_b16 v[154:155], v196 offset:33280
	ds_read_b64_tr_b16 v[156:157], v196 offset:35328
	s_waitcnt lgkmcnt(8)
	v_mfma_f32_32x32x16_bf16 v[80:95], v[158:161], v[110:113], v[80:95]
	v_mfma_f32_32x32x16_bf16 v[64:79], v[162:165], v[110:113], v[64:79]
	ds_read_b64_tr_b16 v[158:159], v196 offset:33792
	ds_read_b64_tr_b16 v[160:161], v196 offset:35840
	ds_read_b64_tr_b16 v[162:163], v196 offset:34304
	ds_read_b64_tr_b16 v[164:165], v196 offset:36352
	s_waitcnt lgkmcnt(10)
	v_mfma_f32_32x32x16_bf16 v[80:95], v[228:231], v[106:109], v[80:95]
	v_mfma_f32_32x32x16_bf16 v[64:79], v[232:235], v[106:109], v[64:79]
	ds_read_b64_tr_b16 v[228:229], v196 offset:36864
	ds_read_b64_tr_b16 v[230:231], v196 offset:38912
	ds_read_b64_tr_b16 v[232:233], v196 offset:37376
	ds_read_b64_tr_b16 v[234:235], v196 offset:39424
	s_waitcnt lgkmcnt(12)
	v_mfma_f32_32x32x16_bf16 v[80:95], v[236:239], v[102:105], v[80:95]
	v_mfma_f32_32x32x16_bf16 v[64:79], v[240:243], v[102:105], v[64:79]
	ds_read_b64_tr_b16 v[236:237], v196 offset:37888
	ds_read_b64_tr_b16 v[238:239], v196 offset:39936
	s_waitcnt lgkmcnt(12)
	v_mfma_f32_32x32x16_bf16 v[0:15], v[166:169], v[150:153], v[0:15]
	ds_read_b64_tr_b16 v[240:241], v196 offset:38400
	ds_read_b64_tr_b16 v[242:243], v196 offset:40448
	s_waitcnt lgkmcnt(12)
	v_mfma_f32_32x32x16_bf16 v[48:63], v[166:169], v[154:157], v[48:63]
	ds_read_b64_tr_b16 v[150:151], v196 offset:40960
	ds_read_b64_tr_b16 v[152:153], v196 offset:43008
	s_waitcnt lgkmcnt(12)
	v_mfma_f32_32x32x16_bf16 v[32:47], v[166:169], v[158:161], v[32:47]
	ds_read_b64_tr_b16 v[154:155], v196 offset:41472
	ds_read_b64_tr_b16 v[156:157], v196 offset:43520
	s_waitcnt lgkmcnt(12)
	v_mfma_f32_32x32x16_bf16 v[16:31], v[166:169], v[162:165], v[16:31]
	ds_read_b64_tr_b16 v[158:159], v196 offset:41984
	ds_read_b64_tr_b16 v[160:161], v196 offset:44032
	s_waitcnt lgkmcnt(12)
	v_mfma_f32_32x32x16_bf16 v[0:15], v[170:173], v[228:231], v[0:15]
	ds_read_b64_tr_b16 v[162:163], v196 offset:42496
	ds_read_b64_tr_b16 v[164:165], v196 offset:44544
	s_waitcnt lgkmcnt(12)
	v_mfma_f32_32x32x16_bf16 v[48:63], v[170:173], v[232:235], v[48:63]
	ds_read_b64_tr_b16 v[228:229], v196 offset:45056
	ds_read_b64_tr_b16 v[230:231], v196 offset:47104
	s_waitcnt lgkmcnt(12)
	v_mfma_f32_32x32x16_bf16 v[32:47], v[170:173], v[236:239], v[32:47]
	ds_read_b64_tr_b16 v[232:233], v196 offset:45568
	ds_read_b64_tr_b16 v[234:235], v196 offset:47616
	s_waitcnt lgkmcnt(12)
	v_mfma_f32_32x32x16_bf16 v[16:31], v[170:173], v[240:243], v[16:31]
	ds_read_b64_tr_b16 v[236:237], v196 offset:46080
	ds_read_b64_tr_b16 v[238:239], v196 offset:48128
	s_waitcnt lgkmcnt(12)
	v_mfma_f32_32x32x16_bf16 v[0:15], v[176:179], v[150:153], v[0:15]
	ds_read_b64_tr_b16 v[240:241], v196 offset:46592
	ds_read_b64_tr_b16 v[242:243], v196 offset:48640
	s_waitcnt lgkmcnt(12)
	v_mfma_f32_32x32x16_bf16 v[48:63], v[176:179], v[154:157], v[48:63]
	s_waitcnt lgkmcnt(10)
	v_mfma_f32_32x32x16_bf16 v[32:47], v[176:179], v[158:161], v[32:47]
	s_waitcnt lgkmcnt(8)
	v_mfma_f32_32x32x16_bf16 v[16:31], v[176:179], v[162:165], v[16:31]
	s_waitcnt lgkmcnt(6)
	v_mfma_f32_32x32x16_bf16 v[0:15], v[180:183], v[228:231], v[0:15]
	s_waitcnt lgkmcnt(4)
	v_mfma_f32_32x32x16_bf16 v[48:63], v[180:183], v[232:235], v[48:63]
	s_waitcnt lgkmcnt(2)
	v_mfma_f32_32x32x16_bf16 v[32:47], v[180:183], v[236:239], v[32:47]
	s_waitcnt lgkmcnt(0)
	v_mfma_f32_32x32x16_bf16 v[16:31], v[180:183], v[240:243], v[16:31]
	s_setprio 0
	s_barrier
; __device__ __forceinline__ void partialSM(f32x16& p0, f32x16& p1, float& m_reg, float& mn, float& alpha) {
;     ...
;   float pmax = p0[0];
; #pragma unroll
;   for (int r = 1; r < 16; ++r) pmax = fmaxf(pmax, p0[r]);
; #pragma unroll
;   for (int r = 0; r < 16; ++r) pmax = fmaxf(pmax, p1[r]);
;   { auto rr = __builtin_amdgcn_permlane32_swap(__float_as_uint(pmax), __float_as_uint(pmax), false, false);
;     pmax = fmaxf(__uint_as_float(rr[0]), __uint_as_float(rr[1])); }
;   if (__builtin_expect(__all(pmax - m_reg <= THR / SCALE), 1)) { mn = m_reg; alpha = 1.f; }
;   else { mn = fmaxf(m_reg, pmax); alpha = __builtin_amdgcn_exp2f((m_reg - mn) * C); m_reg = mn; }
	v_max3_f32 v190, v80, v81, v82
	v_max3_f32 v191, v64, v65, v66
	v_max3_f32 v190, v190, v83, v84
	v_max3_f32 v191, v191, v67, v68
	v_max3_f32 v190, v190, v85, v86
	v_max3_f32 v191, v191, v69, v70
	v_max3_f32 v190, v190, v87, v88
	v_max3_f32 v191, v191, v71, v72
	v_max3_f32 v190, v190, v89, v90
	v_max3_f32 v191, v191, v73, v74
	v_max3_f32 v190, v190, v91, v92
	v_max3_f32 v191, v191, v75, v76
	v_max3_f32 v190, v190, v93, v94
	v_max3_f32 v191, v191, v77, v78
	v_max3_f32 v190, v190, v95, v79
	v_max_f32_e32 v190, v190, v191
	v_sub_f32_e32 v215, v190, v174
	v_cmp_ge_f32_e32 vcc, s86, v215
	s_nop 0
	s_cmp_eq_u64 vcc, exec
	s_cbranch_scc1 .Lda_common_3
	v_mov_b32_e32 v191, v190
	s_nop 1
	v_permlane32_swap_b32_e32 v190, v191
	s_nop 0
	v_max_f32_e32 v212, v190, v191
	v_max_f32_e32 v191, v174, v212
	v_sub_f32_e32 v215, v174, v191
	v_mul_f32_e32 v215, s92, v215
	v_exp_f32_e32 v213, v215
	v_mov_b32_e32 v174, v191
	v_mul_f32_e32 v214, 0xbe0293ee, v174
	v_mul_f32_e32 v175, v175, v213
	s_and_saveexec_b64 s[12:13], s[40:41]
	ds_write_b32 v199, v213 offset:128
	s_or_b64 exec, exec, s[12:13]
	s_waitcnt lgkmcnt(0)
	v_add_u32_e32 v215, v99, v96
	ds_read_b128 v[228:231], v215 offset:128
	ds_read_b128 v[232:235], v215 offset:160
	ds_read_b128 v[236:239], v215 offset:192
	ds_read_b128 v[240:243], v215 offset:224
	s_waitcnt lgkmcnt(0)
	v_pk_mul_f32 v[0:1], v[0:1], v[228:229]
	v_pk_mul_f32 v[2:3], v[2:3], v[230:231]
	v_pk_mul_f32 v[4:5], v[4:5], v[232:233]
	v_pk_mul_f32 v[6:7], v[6:7], v[234:235]
	v_pk_mul_f32 v[8:9], v[8:9], v[236:237]
	v_pk_mul_f32 v[10:11], v[10:11], v[238:239]
	v_pk_mul_f32 v[12:13], v[12:13], v[240:241]
	v_pk_mul_f32 v[14:15], v[14:15], v[242:243]
	v_pk_mul_f32 v[48:49], v[48:49], v[228:229]
	v_pk_mul_f32 v[50:51], v[50:51], v[230:231]
	v_pk_mul_f32 v[52:53], v[52:53], v[232:233]
	v_pk_mul_f32 v[54:55], v[54:55], v[234:235]
	v_pk_mul_f32 v[56:57], v[56:57], v[236:237]
	v_pk_mul_f32 v[58:59], v[58:59], v[238:239]
	v_pk_mul_f32 v[60:61], v[60:61], v[240:241]
	v_pk_mul_f32 v[62:63], v[62:63], v[242:243]
	v_pk_mul_f32 v[32:33], v[32:33], v[228:229]
	v_pk_mul_f32 v[34:35], v[34:35], v[230:231]
	v_pk_mul_f32 v[36:37], v[36:37], v[232:233]
	v_pk_mul_f32 v[38:39], v[38:39], v[234:235]
	v_pk_mul_f32 v[40:41], v[40:41], v[236:237]
	v_pk_mul_f32 v[42:43], v[42:43], v[238:239]
	v_pk_mul_f32 v[44:45], v[44:45], v[240:241]
	v_pk_mul_f32 v[46:47], v[46:47], v[242:243]
	v_pk_mul_f32 v[16:17], v[16:17], v[228:229]
	v_pk_mul_f32 v[18:19], v[18:19], v[230:231]
	v_pk_mul_f32 v[20:21], v[20:21], v[232:233]
	v_pk_mul_f32 v[22:23], v[22:23], v[234:235]
	v_pk_mul_f32 v[24:25], v[24:25], v[236:237]
	v_pk_mul_f32 v[26:27], v[26:27], v[238:239]
	v_pk_mul_f32 v[28:29], v[28:29], v[240:241]
	v_pk_mul_f32 v[30:31], v[30:31], v[242:243]

; #define SBAR() __builtin_amdgcn_sched_barrier(0)
; template <int D0> __device__ __forceinline__ void pv_one(f32x16& od, int vb, bf16x8 pa0, bf16x8 pa1, bf16x8 pa2, bf16x8 pa3) {
;   const s16x4 l0 = tr_read<v_rd_off(D0, 0, 0)>(vb), h0 = tr_read<v_rd_off(D0, 0, 1)>(vb), l1 = tr_read<v_rd_off(D0, 1, 0)>(vb), h1 = tr_read<v_rd_off(D0, 1, 1)>(vb);
;   const s16x4 l2 = tr_read<v_rd_off(D0, 2, 0)>(vb), h2 = tr_read<v_rd_off(D0, 2, 1)>(vb), l3 = tr_read<v_rd_off(D0, 3, 0)>(vb), h3 = tr_read<v_rd_off(D0, 3, 1)>(vb);
;   asm volatile("s_waitcnt lgkmcnt(0)" ::: "memory"); SBAR();
;     ...
;   od = __builtin_amdgcn_mfma_f32_32x32x16_bf16(pa0, PK(l0, h0), od, 0, 0, 0);
;   od = __builtin_amdgcn_mfma_f32_32x32x16_bf16(pa1, PK(l1, h1), od, 0, 0, 0);
;   od = __builtin_amdgcn_mfma_f32_32x32x16_bf16(pa2, PK(l2, h2), od, 0, 0, 0);
;   od = __builtin_amdgcn_mfma_f32_32x32x16_bf16(pa3, PK(l3, h3), od, 0, 0, 0);
;     ...
; }
; __device__ __forceinline__ void pv_d0(f32x16* o, int vb, bf16x8 pa0, bf16x8 pa1, bf16x8 pa2, bf16x8 pa3) {
;   pv_one<0>(o[0], vb, pa0, pa1, pa2, pa3); pv_one<1>(o[1], vb, pa0, pa1, pa2, pa3); pv_one<2>(o[2], vb, pa0, pa1, pa2, pa3); pv_one<3>(o[3], vb, pa0, pa1, pa2, pa3);
; template <int MODE, int SDEPTH>
; __device__ __forceinline__ void attn_unit(const UnitP& u, char* lds) {
;     ...
;   finishSM(pB0, pB1, alB, l_reg, pa0, pa1, pa2, pa3); SBAR();
;   pv_d0(o, vb0 + (int)SHM_V, pa0, pa1, pa2, pa3);
.Lda_skipk_3:
	s_barrier
	s_cmp_lt_u32 s31, 132
	s_cbranch_scc1 .Lda_loop
	s_setprio 3
	ds_read_b64_tr_b16 v[150:151], v196 offset:49152
	ds_read_b64_tr_b16 v[152:153], v196 offset:51200
	ds_read_b64_tr_b16 v[154:155], v196 offset:49664
	ds_read_b64_tr_b16 v[156:157], v196 offset:51712
	ds_read_b64_tr_b16 v[158:159], v196 offset:50176
	ds_read_b64_tr_b16 v[160:161], v196 offset:52224
	ds_read_b64_tr_b16 v[162:163], v196 offset:50688
	ds_read_b64_tr_b16 v[164:165], v196 offset:52736
	ds_read_b64_tr_b16 v[228:229], v196 offset:53248
	ds_read_b64_tr_b16 v[230:231], v196 offset:55296
	ds_read_b64_tr_b16 v[232:233], v196 offset:53760
	ds_read_b64_tr_b16 v[234:235], v196 offset:55808
	ds_read_b64_tr_b16 v[236:237], v196 offset:54272
	ds_read_b64_tr_b16 v[238:239], v196 offset:56320
	s_waitcnt lgkmcnt(12)
	v_mfma_f32_32x32x16_bf16 v[0:15], v[166:169], v[150:153], v[0:15]
	ds_read_b64_tr_b16 v[240:241], v196 offset:54784
	ds_read_b64_tr_b16 v[242:243], v196 offset:56832
	s_waitcnt lgkmcnt(12)
	v_mfma_f32_32x32x16_bf16 v[48:63], v[166:169], v[154:157], v[48:63]
	ds_read_b64_tr_b16 v[150:151], v196 offset:57344
	ds_read_b64_tr_b16 v[152:153], v196 offset:59392
	s_waitcnt lgkmcnt(12)
	v_mfma_f32_32x32x16_bf16 v[32:47], v[166:169], v[158:161], v[32:47]
	ds_read_b64_tr_b16 v[154:155], v196 offset:57856
	ds_read_b64_tr_b16 v[156:157], v196 offset:59904
	s_waitcnt lgkmcnt(12)
	v_mfma_f32_32x32x16_bf16 v[16:31], v[166:169], v[162:165], v[16:31]
	ds_read_b64_tr_b16 v[158:159], v196 offset:58368
	ds_read_b64_tr_b16 v[160:161], v196 offset:60416
	s_waitcnt lgkmcnt(12)
	v_mfma_f32_32x32x16_bf16 v[0:15], v[170:173], v[228:231], v[0:15]
	ds_read_b64_tr_b16 v[162:163], v196 offset:58880
	ds_read_b64_tr_b16 v[164:165], v196 offset:60928
	s_waitcnt lgkmcnt(12)
	v_mfma_f32_32x32x16_bf16 v[48:63], v[170:173], v[232:235], v[48:63]
	ds_read_b64_tr_b16 v[228:229], v196 offset:61440
	ds_read_b64_tr_b16 v[230:231], v196 offset:63488
	s_waitcnt lgkmcnt(12)
	v_mfma_f32_32x32x16_bf16 v[32:47], v[170:173], v[236:239], v[32:47]
	ds_read_b64_tr_b16 v[232:233], v196 offset:61952
	ds_read_b64_tr_b16 v[234:235], v196 offset:64000
	s_waitcnt lgkmcnt(12)
	v_mfma_f32_32x32x16_bf16 v[16:31], v[170:173], v[240:243], v[16:31]
	ds_read_b64_tr_b16 v[236:237], v196 offset:62464
	ds_read_b64_tr_b16 v[238:239], v196 offset:64512
	s_waitcnt lgkmcnt(12)
	v_mfma_f32_32x32x16_bf16 v[0:15], v[176:179], v[150:153], v[0:15]
	ds_read_b64_tr_b16 v[240:241], v196 offset:62976
	ds_read_b64_tr_b16 v[242:243], v196 offset:65024
	s_waitcnt lgkmcnt(12)
	v_mfma_f32_32x32x16_bf16 v[48:63], v[176:179], v[154:157], v[48:63]
	s_waitcnt lgkmcnt(10)
	v_mfma_f32_32x32x16_bf16 v[32:47], v[176:179], v[158:161], v[32:47]
	s_waitcnt lgkmcnt(8)
	v_mfma_f32_32x32x16_bf16 v[16:31], v[176:179], v[162:165], v[16:31]
	s_waitcnt lgkmcnt(6)
	v_mfma_f32_32x32x16_bf16 v[0:15], v[180:183], v[228:231], v[0:15]
	s_waitcnt lgkmcnt(4)
	v_mfma_f32_32x32x16_bf16 v[48:63], v[180:183], v[232:235], v[48:63]
	s_waitcnt lgkmcnt(2)
	v_mfma_f32_32x32x16_bf16 v[32:47], v[180:183], v[236:239], v[32:47]
	s_waitcnt lgkmcnt(0)
	v_mfma_f32_32x32x16_bf16 v[16:31], v[180:183], v[240:243], v[16:31]
	s_nop 12
	s_setprio 0
	s_cmp_lt_u32 s36, 4
	s_cbranch_scc0 .Lda_trail
	s_barrier
